# adds hand-written batched-load epilogue for the q|k|gates tiles of the second input projection (rotary tables loaded per 4 row groups instead of per row group with full waits)
# baseline (speedup 1.0000x reference)
.LBB0_503:
.LBB0_504:
	s_cmp_lt_i32 s50, 8
	s_cselect_b64 s[4:5], -1, 0
	s_movk_i32 s26, 0x880
	s_cselect_b32 s26, s26, 0x800
	s_cselect_b32 s42, s97, s61
	s_cselect_b32 s43, s60, s62
	s_cselect_b32 s27, 0, -8
	s_and_b64 s[4:5], s[4:5], s[28:29]
	s_add_i32 s27, s27, s50
	v_lshl_or_b32 v128, s27, 8, v160
	v_mad_u32_u24 v128, v156, s26, v128
	v_lshlrev_b32_e32 v128, 1, v128
	s_lshl_b32 s73, s26, 5
	s_and_b64 vcc, exec, s[4:5]
	s_cbranch_vccnz .Linb_rope
	v_cvt_pk_bf16_f32 v124, v124, v125
	v_cvt_pk_bf16_f32 v125, v126, v127
	v_cvt_pk_bf16_f32 v126, v120, v121
	v_cvt_pk_bf16_f32 v127, v122, v123
	global_store_dwordx4 v128, v[124:127], s[42:43] offset:0
	v_cvt_pk_bf16_f32 v116, v116, v117
	v_cvt_pk_bf16_f32 v117, v118, v119
	v_cvt_pk_bf16_f32 v118, v112, v113
	v_cvt_pk_bf16_f32 v119, v114, v115
	global_store_dwordx4 v128, v[116:119], s[42:43] offset:256
	s_mul_i32 s4, s73, 1
	v_add_u32_e32 v132, s4, v128
	v_cvt_pk_bf16_f32 v108, v108, v109
	v_cvt_pk_bf16_f32 v109, v110, v111
	v_cvt_pk_bf16_f32 v110, v104, v105
	v_cvt_pk_bf16_f32 v111, v106, v107
	global_store_dwordx4 v132, v[108:111], s[42:43] offset:0
	v_cvt_pk_bf16_f32 v100, v100, v101
	v_cvt_pk_bf16_f32 v101, v102, v103
	v_cvt_pk_bf16_f32 v102, v96, v97
	v_cvt_pk_bf16_f32 v103, v98, v99
	global_store_dwordx4 v132, v[100:103], s[42:43] offset:256
	s_mul_i32 s4, s73, 2
	v_add_u32_e32 v132, s4, v128
	v_cvt_pk_bf16_f32 v92, v92, v93
	v_cvt_pk_bf16_f32 v93, v94, v95
	v_cvt_pk_bf16_f32 v94, v88, v89
	v_cvt_pk_bf16_f32 v95, v90, v91
	global_store_dwordx4 v132, v[92:95], s[42:43] offset:0
	v_cvt_pk_bf16_f32 v84, v84, v85
	v_cvt_pk_bf16_f32 v85, v86, v87
	v_cvt_pk_bf16_f32 v86, v80, v81
	v_cvt_pk_bf16_f32 v87, v82, v83
	global_store_dwordx4 v132, v[84:87], s[42:43] offset:256
	s_mul_i32 s4, s73, 3
	v_add_u32_e32 v132, s4, v128
	v_cvt_pk_bf16_f32 v76, v76, v77
	v_cvt_pk_bf16_f32 v77, v78, v79
	v_cvt_pk_bf16_f32 v78, v72, v73
	v_cvt_pk_bf16_f32 v79, v74, v75
	global_store_dwordx4 v132, v[76:79], s[42:43] offset:0
	v_cvt_pk_bf16_f32 v68, v68, v69
	v_cvt_pk_bf16_f32 v69, v70, v71
	v_cvt_pk_bf16_f32 v70, v64, v65
	v_cvt_pk_bf16_f32 v71, v66, v67
	global_store_dwordx4 v132, v[68:71], s[42:43] offset:256
	s_mul_i32 s4, s73, 8
	v_add_u32_e32 v132, s4, v128
	v_cvt_pk_bf16_f32 v60, v60, v61
	v_cvt_pk_bf16_f32 v61, v62, v63
	v_cvt_pk_bf16_f32 v62, v56, v57
	v_cvt_pk_bf16_f32 v63, v58, v59
	global_store_dwordx4 v132, v[60:63], s[42:43] offset:0
	v_cvt_pk_bf16_f32 v52, v52, v53
	v_cvt_pk_bf16_f32 v53, v54, v55
	v_cvt_pk_bf16_f32 v54, v48, v49
	v_cvt_pk_bf16_f32 v55, v50, v51
	global_store_dwordx4 v132, v[52:55], s[42:43] offset:256
	s_mul_i32 s4, s73, 9
	v_add_u32_e32 v132, s4, v128
	v_cvt_pk_bf16_f32 v44, v44, v45
	v_cvt_pk_bf16_f32 v45, v46, v47
	v_cvt_pk_bf16_f32 v46, v40, v41
	v_cvt_pk_bf16_f32 v47, v42, v43
	global_store_dwordx4 v132, v[44:47], s[42:43] offset:0
	v_cvt_pk_bf16_f32 v36, v36, v37
	v_cvt_pk_bf16_f32 v37, v38, v39
	v_cvt_pk_bf16_f32 v38, v32, v33
	v_cvt_pk_bf16_f32 v39, v34, v35
	global_store_dwordx4 v132, v[36:39], s[42:43] offset:256
	s_mul_i32 s4, s73, 10
	v_add_u32_e32 v132, s4, v128
	v_cvt_pk_bf16_f32 v28, v28, v29
	v_cvt_pk_bf16_f32 v29, v30, v31
	v_cvt_pk_bf16_f32 v30, v24, v25
	v_cvt_pk_bf16_f32 v31, v26, v27
	global_store_dwordx4 v132, v[28:31], s[42:43] offset:0
	v_cvt_pk_bf16_f32 v20, v20, v21
	v_cvt_pk_bf16_f32 v21, v22, v23
	v_cvt_pk_bf16_f32 v22, v16, v17
	v_cvt_pk_bf16_f32 v23, v18, v19
	global_store_dwordx4 v132, v[20:23], s[42:43] offset:256
	s_mul_i32 s4, s73, 11
	v_add_u32_e32 v132, s4, v128
	v_cvt_pk_bf16_f32 v12, v12, v13
	v_cvt_pk_bf16_f32 v13, v14, v15
	v_cvt_pk_bf16_f32 v14, v8, v9
	v_cvt_pk_bf16_f32 v15, v10, v11
	global_store_dwordx4 v132, v[12:15], s[42:43] offset:0
	v_cvt_pk_bf16_f32 v4, v4, v5
	v_cvt_pk_bf16_f32 v5, v6, v7
	v_cvt_pk_bf16_f32 v6, v0, v1
	v_cvt_pk_bf16_f32 v7, v2, v3
	global_store_dwordx4 v132, v[4:7], s[42:43] offset:256
	s_branch .Linb_done
.Linb_rope:
	v_lshlrev_b32_e32 v129, 5, v156
	v_and_b32_e32 v129, 0xffe0, v129
	v_mov_b32_e32 v133, 0x80000000
	v_cndmask_b32_e64 v130, 0, v133, s[38:39]
	v_and_b32_e32 v133, 64, v240
	v_xor_b32_e32 v132, 16, v240
	v_add_u32_e32 v133, 64, v133
	v_cmp_lt_i32_e32 vcc, v132, v133
	s_nop 1
	v_cndmask_b32_e32 v132, v240, v132, vcc
	v_lshlrev_b32_e32 v131, 2, v132
	global_load_dwordx4 v[148:151], v129, s[10:11] offset:0
	global_load_dwordx4 v[152:155], v129, s[10:11] offset:16
	global_load_dwordx4 v[164:167], v129, s[12:13] offset:0
	global_load_dwordx4 v[168:171], v129, s[12:13] offset:16
	global_load_dwordx4 v[172:175], v129, s[10:11] offset:512
	global_load_dwordx4 v[176:179], v129, s[10:11] offset:528
	global_load_dwordx4 v[180:183], v129, s[12:13] offset:512
	global_load_dwordx4 v[184:187], v129, s[12:13] offset:528
	global_load_dwordx4 v[188:191], v129, s[10:11] offset:1024
	global_load_dwordx4 v[208:211], v129, s[10:11] offset:1040
	global_load_dwordx4 v[212:215], v129, s[12:13] offset:1024
	global_load_dwordx4 v[216:219], v129, s[12:13] offset:1040
	global_load_dwordx4 v[220:223], v129, s[10:11] offset:1536
	global_load_dwordx4 v[224:227], v129, s[10:11] offset:1552
	global_load_dwordx4 v[228:231], v129, s[12:13] offset:1536
	global_load_dwordx4 v[232:235], v129, s[12:13] offset:1552
	ds_bpermute_b32 v134, v131, v124
	ds_bpermute_b32 v135, v131, v125
	ds_bpermute_b32 v146, v131, v126
	ds_bpermute_b32 v147, v131, v127
	ds_bpermute_b32 v156, v131, v120
	ds_bpermute_b32 v157, v131, v121
	ds_bpermute_b32 v162, v131, v122
	ds_bpermute_b32 v163, v131, v123
	s_waitcnt vmcnt(12)
	v_cndmask_b32_e64 v148, v148, 1.0, s[40:41]
	v_cndmask_b32_e64 v149, v149, 1.0, s[40:41]
	v_cndmask_b32_e64 v150, v150, 1.0, s[40:41]
	v_cndmask_b32_e64 v151, v151, 1.0, s[40:41]
	v_cndmask_b32_e64 v152, v152, 1.0, s[40:41]
	v_cndmask_b32_e64 v153, v153, 1.0, s[40:41]
	v_cndmask_b32_e64 v154, v154, 1.0, s[40:41]
	v_cndmask_b32_e64 v155, v155, 1.0, s[40:41]
	v_xor_b32_e32 v164, v130, v164
	v_cndmask_b32_e64 v164, v164, 0, s[40:41]
	v_xor_b32_e32 v165, v130, v165
	v_cndmask_b32_e64 v165, v165, 0, s[40:41]
	v_xor_b32_e32 v166, v130, v166
	v_cndmask_b32_e64 v166, v166, 0, s[40:41]
	v_xor_b32_e32 v167, v130, v167
	v_cndmask_b32_e64 v167, v167, 0, s[40:41]
	v_xor_b32_e32 v168, v130, v168
	v_cndmask_b32_e64 v168, v168, 0, s[40:41]
	v_xor_b32_e32 v169, v130, v169
	v_cndmask_b32_e64 v169, v169, 0, s[40:41]
	v_xor_b32_e32 v170, v130, v170
	v_cndmask_b32_e64 v170, v170, 0, s[40:41]
	v_xor_b32_e32 v171, v130, v171
	v_cndmask_b32_e64 v171, v171, 0, s[40:41]
	s_waitcnt lgkmcnt(0)
	v_mul_f32_e32 v134, v164, v134
	v_mul_f32_e32 v135, v165, v135
	v_mul_f32_e32 v146, v166, v146
	v_mul_f32_e32 v147, v167, v147
	v_mul_f32_e32 v156, v168, v156
	v_mul_f32_e32 v157, v169, v157
	v_mul_f32_e32 v162, v170, v162
	v_mul_f32_e32 v163, v171, v163
	v_fma_f32 v124, v124, v148, v134
	v_fma_f32 v125, v125, v149, v135
	v_fma_f32 v126, v126, v150, v146
	v_fma_f32 v127, v127, v151, v147
	v_fma_f32 v120, v120, v152, v156
	v_fma_f32 v121, v121, v153, v157
	v_fma_f32 v122, v122, v154, v162
	v_fma_f32 v123, v123, v155, v163
	ds_bpermute_b32 v134, v131, v116
	ds_bpermute_b32 v135, v131, v117
	ds_bpermute_b32 v146, v131, v118
	ds_bpermute_b32 v147, v131, v119
	ds_bpermute_b32 v156, v131, v112
	ds_bpermute_b32 v157, v131, v113
	ds_bpermute_b32 v162, v131, v114
	ds_bpermute_b32 v163, v131, v115
	v_cvt_pk_bf16_f32 v124, v124, v125
	v_cvt_pk_bf16_f32 v125, v126, v127
	v_cvt_pk_bf16_f32 v126, v120, v121
	v_cvt_pk_bf16_f32 v127, v122, v123
	global_store_dwordx4 v128, v[124:127], s[42:43] offset:0
	s_waitcnt lgkmcnt(0)
	v_mul_f32_e32 v134, v164, v134
	v_mul_f32_e32 v135, v165, v135
	v_mul_f32_e32 v146, v166, v146
	v_mul_f32_e32 v147, v167, v147
	v_mul_f32_e32 v156, v168, v156
	v_mul_f32_e32 v157, v169, v157
	v_mul_f32_e32 v162, v170, v162
	v_mul_f32_e32 v163, v171, v163
	v_fma_f32 v116, v116, v148, v134
	v_fma_f32 v117, v117, v149, v135
	v_fma_f32 v118, v118, v150, v146
	v_fma_f32 v119, v119, v151, v147
	v_fma_f32 v112, v112, v152, v156
	v_fma_f32 v113, v113, v153, v157
	v_fma_f32 v114, v114, v154, v162
	v_fma_f32 v115, v115, v155, v163
	v_cvt_pk_bf16_f32 v116, v116, v117
	v_cvt_pk_bf16_f32 v117, v118, v119
	v_cvt_pk_bf16_f32 v118, v112, v113
	v_cvt_pk_bf16_f32 v119, v114, v115
	global_store_dwordx4 v128, v[116:119], s[42:43] offset:256
	ds_bpermute_b32 v134, v131, v108
	ds_bpermute_b32 v135, v131, v109
	ds_bpermute_b32 v146, v131, v110
	ds_bpermute_b32 v147, v131, v111
	ds_bpermute_b32 v156, v131, v104
	ds_bpermute_b32 v157, v131, v105
	ds_bpermute_b32 v162, v131, v106
	ds_bpermute_b32 v163, v131, v107
	s_waitcnt vmcnt(10)
	v_cndmask_b32_e64 v172, v172, 1.0, s[40:41]
	v_cndmask_b32_e64 v173, v173, 1.0, s[40:41]
	v_cndmask_b32_e64 v174, v174, 1.0, s[40:41]
	v_cndmask_b32_e64 v175, v175, 1.0, s[40:41]
	v_cndmask_b32_e64 v176, v176, 1.0, s[40:41]
	v_cndmask_b32_e64 v177, v177, 1.0, s[40:41]
	v_cndmask_b32_e64 v178, v178, 1.0, s[40:41]
	v_cndmask_b32_e64 v179, v179, 1.0, s[40:41]
	v_xor_b32_e32 v180, v130, v180
	v_cndmask_b32_e64 v180, v180, 0, s[40:41]
	v_xor_b32_e32 v181, v130, v181
	v_cndmask_b32_e64 v181, v181, 0, s[40:41]
	v_xor_b32_e32 v182, v130, v182
	v_cndmask_b32_e64 v182, v182, 0, s[40:41]
	v_xor_b32_e32 v183, v130, v183
	v_cndmask_b32_e64 v183, v183, 0, s[40:41]
	v_xor_b32_e32 v184, v130, v184
	v_cndmask_b32_e64 v184, v184, 0, s[40:41]
	v_xor_b32_e32 v185, v130, v185
	v_cndmask_b32_e64 v185, v185, 0, s[40:41]
	v_xor_b32_e32 v186, v130, v186
	v_cndmask_b32_e64 v186, v186, 0, s[40:41]
	v_xor_b32_e32 v187, v130, v187
	v_cndmask_b32_e64 v187, v187, 0, s[40:41]
	s_mul_i32 s4, s73, 1
	v_add_u32_e32 v132, s4, v128
	s_waitcnt lgkmcnt(0)
	v_mul_f32_e32 v134, v180, v134
	v_mul_f32_e32 v135, v181, v135
	v_mul_f32_e32 v146, v182, v146
	v_mul_f32_e32 v147, v183, v147
	v_mul_f32_e32 v156, v184, v156
	v_mul_f32_e32 v157, v185, v157
	v_mul_f32_e32 v162, v186, v162
	v_mul_f32_e32 v163, v187, v163
	v_fma_f32 v108, v108, v172, v134
	v_fma_f32 v109, v109, v173, v135
	v_fma_f32 v110, v110, v174, v146
	v_fma_f32 v111, v111, v175, v147
	v_fma_f32 v104, v104, v176, v156
	v_fma_f32 v105, v105, v177, v157
	v_fma_f32 v106, v106, v178, v162
	v_fma_f32 v107, v107, v179, v163
	ds_bpermute_b32 v134, v131, v100
	ds_bpermute_b32 v135, v131, v101
	ds_bpermute_b32 v146, v131, v102
	ds_bpermute_b32 v147, v131, v103
	ds_bpermute_b32 v156, v131, v96
	ds_bpermute_b32 v157, v131, v97
	ds_bpermute_b32 v162, v131, v98
	ds_bpermute_b32 v163, v131, v99
	v_cvt_pk_bf16_f32 v108, v108, v109
	v_cvt_pk_bf16_f32 v109, v110, v111
	v_cvt_pk_bf16_f32 v110, v104, v105
	v_cvt_pk_bf16_f32 v111, v106, v107
	global_store_dwordx4 v132, v[108:111], s[42:43] offset:0
	s_waitcnt lgkmcnt(0)
	v_mul_f32_e32 v134, v180, v134
	v_mul_f32_e32 v135, v181, v135
	v_mul_f32_e32 v146, v182, v146
	v_mul_f32_e32 v147, v183, v147
	v_mul_f32_e32 v156, v184, v156
	v_mul_f32_e32 v157, v185, v157
	v_mul_f32_e32 v162, v186, v162
	v_mul_f32_e32 v163, v187, v163
	v_fma_f32 v100, v100, v172, v134
	v_fma_f32 v101, v101, v173, v135
	v_fma_f32 v102, v102, v174, v146
	v_fma_f32 v103, v103, v175, v147
	v_fma_f32 v96, v96, v176, v156
	v_fma_f32 v97, v97, v177, v157
	v_fma_f32 v98, v98, v178, v162
	v_fma_f32 v99, v99, v179, v163
	v_cvt_pk_bf16_f32 v100, v100, v101
	v_cvt_pk_bf16_f32 v101, v102, v103
	v_cvt_pk_bf16_f32 v102, v96, v97
	v_cvt_pk_bf16_f32 v103, v98, v99
	global_store_dwordx4 v132, v[100:103], s[42:43] offset:256
	ds_bpermute_b32 v134, v131, v92
	ds_bpermute_b32 v135, v131, v93
	ds_bpermute_b32 v146, v131, v94
	ds_bpermute_b32 v147, v131, v95
	ds_bpermute_b32 v156, v131, v88
	ds_bpermute_b32 v157, v131, v89
	ds_bpermute_b32 v162, v131, v90
	ds_bpermute_b32 v163, v131, v91
	s_waitcnt vmcnt(8)
	v_cndmask_b32_e64 v188, v188, 1.0, s[40:41]
	v_cndmask_b32_e64 v189, v189, 1.0, s[40:41]
	v_cndmask_b32_e64 v190, v190, 1.0, s[40:41]
	v_cndmask_b32_e64 v191, v191, 1.0, s[40:41]
	v_cndmask_b32_e64 v208, v208, 1.0, s[40:41]
	v_cndmask_b32_e64 v209, v209, 1.0, s[40:41]
	v_cndmask_b32_e64 v210, v210, 1.0, s[40:41]
	v_cndmask_b32_e64 v211, v211, 1.0, s[40:41]
	v_xor_b32_e32 v212, v130, v212
	v_cndmask_b32_e64 v212, v212, 0, s[40:41]
	v_xor_b32_e32 v213, v130, v213
	v_cndmask_b32_e64 v213, v213, 0, s[40:41]
	v_xor_b32_e32 v214, v130, v214
	v_cndmask_b32_e64 v214, v214, 0, s[40:41]
	v_xor_b32_e32 v215, v130, v215
	v_cndmask_b32_e64 v215, v215, 0, s[40:41]
	v_xor_b32_e32 v216, v130, v216
	v_cndmask_b32_e64 v216, v216, 0, s[40:41]
	v_xor_b32_e32 v217, v130, v217
	v_cndmask_b32_e64 v217, v217, 0, s[40:41]
	v_xor_b32_e32 v218, v130, v218
	v_cndmask_b32_e64 v218, v218, 0, s[40:41]
	v_xor_b32_e32 v219, v130, v219
	v_cndmask_b32_e64 v219, v219, 0, s[40:41]
	s_mul_i32 s4, s73, 2
	v_add_u32_e32 v132, s4, v128
	s_waitcnt lgkmcnt(0)
	v_mul_f32_e32 v134, v212, v134
	v_mul_f32_e32 v135, v213, v135
	v_mul_f32_e32 v146, v214, v146
	v_mul_f32_e32 v147, v215, v147
	v_mul_f32_e32 v156, v216, v156
	v_mul_f32_e32 v157, v217, v157
	v_mul_f32_e32 v162, v218, v162
	v_mul_f32_e32 v163, v219, v163
	v_fma_f32 v92, v92, v188, v134
	v_fma_f32 v93, v93, v189, v135
	v_fma_f32 v94, v94, v190, v146
	v_fma_f32 v95, v95, v191, v147
	v_fma_f32 v88, v88, v208, v156
	v_fma_f32 v89, v89, v209, v157
	v_fma_f32 v90, v90, v210, v162
	v_fma_f32 v91, v91, v211, v163
	ds_bpermute_b32 v134, v131, v84
	ds_bpermute_b32 v135, v131, v85
	ds_bpermute_b32 v146, v131, v86
	ds_bpermute_b32 v147, v131, v87
	ds_bpermute_b32 v156, v131, v80
	ds_bpermute_b32 v157, v131, v81
	ds_bpermute_b32 v162, v131, v82
	ds_bpermute_b32 v163, v131, v83
	v_cvt_pk_bf16_f32 v92, v92, v93
	v_cvt_pk_bf16_f32 v93, v94, v95
	v_cvt_pk_bf16_f32 v94, v88, v89
	v_cvt_pk_bf16_f32 v95, v90, v91
	global_store_dwordx4 v132, v[92:95], s[42:43] offset:0
	s_waitcnt lgkmcnt(0)
	v_mul_f32_e32 v134, v212, v134
	v_mul_f32_e32 v135, v213, v135
	v_mul_f32_e32 v146, v214, v146
	v_mul_f32_e32 v147, v215, v147
	v_mul_f32_e32 v156, v216, v156
	v_mul_f32_e32 v157, v217, v157
	v_mul_f32_e32 v162, v218, v162
	v_mul_f32_e32 v163, v219, v163
	v_fma_f32 v84, v84, v188, v134
	v_fma_f32 v85, v85, v189, v135
	v_fma_f32 v86, v86, v190, v146
	v_fma_f32 v87, v87, v191, v147
	v_fma_f32 v80, v80, v208, v156
	v_fma_f32 v81, v81, v209, v157
	v_fma_f32 v82, v82, v210, v162
	v_fma_f32 v83, v83, v211, v163
	v_cvt_pk_bf16_f32 v84, v84, v85
	v_cvt_pk_bf16_f32 v85, v86, v87
	v_cvt_pk_bf16_f32 v86, v80, v81
	v_cvt_pk_bf16_f32 v87, v82, v83
	global_store_dwordx4 v132, v[84:87], s[42:43] offset:256
	ds_bpermute_b32 v134, v131, v76
	ds_bpermute_b32 v135, v131, v77
	ds_bpermute_b32 v146, v131, v78
	ds_bpermute_b32 v147, v131, v79
	ds_bpermute_b32 v156, v131, v72
	ds_bpermute_b32 v157, v131, v73
	ds_bpermute_b32 v162, v131, v74
	ds_bpermute_b32 v163, v131, v75
	s_waitcnt vmcnt(6)
	v_cndmask_b32_e64 v220, v220, 1.0, s[40:41]
	v_cndmask_b32_e64 v221, v221, 1.0, s[40:41]
	v_cndmask_b32_e64 v222, v222, 1.0, s[40:41]
	v_cndmask_b32_e64 v223, v223, 1.0, s[40:41]
	v_cndmask_b32_e64 v224, v224, 1.0, s[40:41]
	v_cndmask_b32_e64 v225, v225, 1.0, s[40:41]
	v_cndmask_b32_e64 v226, v226, 1.0, s[40:41]
	v_cndmask_b32_e64 v227, v227, 1.0, s[40:41]
	v_xor_b32_e32 v228, v130, v228
	v_cndmask_b32_e64 v228, v228, 0, s[40:41]
	v_xor_b32_e32 v229, v130, v229
	v_cndmask_b32_e64 v229, v229, 0, s[40:41]
	v_xor_b32_e32 v230, v130, v230
	v_cndmask_b32_e64 v230, v230, 0, s[40:41]
	v_xor_b32_e32 v231, v130, v231
	v_cndmask_b32_e64 v231, v231, 0, s[40:41]
	v_xor_b32_e32 v232, v130, v232
	v_cndmask_b32_e64 v232, v232, 0, s[40:41]
	v_xor_b32_e32 v233, v130, v233
	v_cndmask_b32_e64 v233, v233, 0, s[40:41]
	v_xor_b32_e32 v234, v130, v234
	v_cndmask_b32_e64 v234, v234, 0, s[40:41]
	v_xor_b32_e32 v235, v130, v235
	v_cndmask_b32_e64 v235, v235, 0, s[40:41]
	s_mul_i32 s4, s73, 3
	v_add_u32_e32 v132, s4, v128
	s_waitcnt lgkmcnt(0)
	v_mul_f32_e32 v134, v228, v134
	v_mul_f32_e32 v135, v229, v135
	v_mul_f32_e32 v146, v230, v146
	v_mul_f32_e32 v147, v231, v147
	v_mul_f32_e32 v156, v232, v156
	v_mul_f32_e32 v157, v233, v157
	v_mul_f32_e32 v162, v234, v162
	v_mul_f32_e32 v163, v235, v163
	v_fma_f32 v76, v76, v220, v134
	v_fma_f32 v77, v77, v221, v135
	v_fma_f32 v78, v78, v222, v146
	v_fma_f32 v79, v79, v223, v147
	v_fma_f32 v72, v72, v224, v156
	v_fma_f32 v73, v73, v225, v157
	v_fma_f32 v74, v74, v226, v162
	v_fma_f32 v75, v75, v227, v163
	ds_bpermute_b32 v134, v131, v68
	ds_bpermute_b32 v135, v131, v69
	ds_bpermute_b32 v146, v131, v70
	ds_bpermute_b32 v147, v131, v71
	ds_bpermute_b32 v156, v131, v64
	ds_bpermute_b32 v157, v131, v65
	ds_bpermute_b32 v162, v131, v66
	ds_bpermute_b32 v163, v131, v67
	v_cvt_pk_bf16_f32 v76, v76, v77
	v_cvt_pk_bf16_f32 v77, v78, v79
	v_cvt_pk_bf16_f32 v78, v72, v73
	v_cvt_pk_bf16_f32 v79, v74, v75
	global_store_dwordx4 v132, v[76:79], s[42:43] offset:0
	s_waitcnt lgkmcnt(0)
	v_mul_f32_e32 v134, v228, v134
	v_mul_f32_e32 v135, v229, v135
	v_mul_f32_e32 v146, v230, v146
	v_mul_f32_e32 v147, v231, v147
	v_mul_f32_e32 v156, v232, v156
	v_mul_f32_e32 v157, v233, v157
	v_mul_f32_e32 v162, v234, v162
	v_mul_f32_e32 v163, v235, v163
	v_fma_f32 v68, v68, v220, v134
	v_fma_f32 v69, v69, v221, v135
	v_fma_f32 v70, v70, v222, v146
	v_fma_f32 v71, v71, v223, v147
	v_fma_f32 v64, v64, v224, v156
	v_fma_f32 v65, v65, v225, v157
	v_fma_f32 v66, v66, v226, v162
	v_fma_f32 v67, v67, v227, v163
	v_cvt_pk_bf16_f32 v68, v68, v69
	v_cvt_pk_bf16_f32 v69, v70, v71
	v_cvt_pk_bf16_f32 v70, v64, v65
	v_cvt_pk_bf16_f32 v71, v66, v67
	global_store_dwordx4 v132, v[68:71], s[42:43] offset:256
	v_add_u32_e32 v133, 0x1000, v129
	global_load_dwordx4 v[148:151], v133, s[10:11] offset:0
	global_load_dwordx4 v[152:155], v133, s[10:11] offset:16
	global_load_dwordx4 v[164:167], v133, s[12:13] offset:0
	global_load_dwordx4 v[168:171], v133, s[12:13] offset:16
	global_load_dwordx4 v[172:175], v133, s[10:11] offset:512
	global_load_dwordx4 v[176:179], v133, s[10:11] offset:528
	global_load_dwordx4 v[180:183], v133, s[12:13] offset:512
	global_load_dwordx4 v[184:187], v133, s[12:13] offset:528
	global_load_dwordx4 v[188:191], v133, s[10:11] offset:1024
	global_load_dwordx4 v[208:211], v133, s[10:11] offset:1040
	global_load_dwordx4 v[212:215], v133, s[12:13] offset:1024
	global_load_dwordx4 v[216:219], v133, s[12:13] offset:1040
	global_load_dwordx4 v[220:223], v133, s[10:11] offset:1536
	global_load_dwordx4 v[224:227], v133, s[10:11] offset:1552
	global_load_dwordx4 v[228:231], v133, s[12:13] offset:1536
	global_load_dwordx4 v[232:235], v133, s[12:13] offset:1552
	ds_bpermute_b32 v134, v131, v60
	ds_bpermute_b32 v135, v131, v61
	ds_bpermute_b32 v146, v131, v62
	ds_bpermute_b32 v147, v131, v63
	ds_bpermute_b32 v156, v131, v56
	ds_bpermute_b32 v157, v131, v57
	ds_bpermute_b32 v162, v131, v58
	ds_bpermute_b32 v163, v131, v59
	s_waitcnt vmcnt(12)
	v_cndmask_b32_e64 v148, v148, 1.0, s[40:41]
	v_cndmask_b32_e64 v149, v149, 1.0, s[40:41]
	v_cndmask_b32_e64 v150, v150, 1.0, s[40:41]
	v_cndmask_b32_e64 v151, v151, 1.0, s[40:41]
	v_cndmask_b32_e64 v152, v152, 1.0, s[40:41]
	v_cndmask_b32_e64 v153, v153, 1.0, s[40:41]
	v_cndmask_b32_e64 v154, v154, 1.0, s[40:41]
	v_cndmask_b32_e64 v155, v155, 1.0, s[40:41]
	v_xor_b32_e32 v164, v130, v164
	v_cndmask_b32_e64 v164, v164, 0, s[40:41]
	v_xor_b32_e32 v165, v130, v165
	v_cndmask_b32_e64 v165, v165, 0, s[40:41]
	v_xor_b32_e32 v166, v130, v166
	v_cndmask_b32_e64 v166, v166, 0, s[40:41]
	v_xor_b32_e32 v167, v130, v167
	v_cndmask_b32_e64 v167, v167, 0, s[40:41]
	v_xor_b32_e32 v168, v130, v168
	v_cndmask_b32_e64 v168, v168, 0, s[40:41]
	v_xor_b32_e32 v169, v130, v169
	v_cndmask_b32_e64 v169, v169, 0, s[40:41]
	v_xor_b32_e32 v170, v130, v170
	v_cndmask_b32_e64 v170, v170, 0, s[40:41]
	v_xor_b32_e32 v171, v130, v171
	v_cndmask_b32_e64 v171, v171, 0, s[40:41]
	s_mul_i32 s4, s73, 8
	v_add_u32_e32 v132, s4, v128
	s_waitcnt lgkmcnt(0)
	v_mul_f32_e32 v134, v164, v134
	v_mul_f32_e32 v135, v165, v135
	v_mul_f32_e32 v146, v166, v146
	v_mul_f32_e32 v147, v167, v147
	v_mul_f32_e32 v156, v168, v156
	v_mul_f32_e32 v157, v169, v157
	v_mul_f32_e32 v162, v170, v162
	v_mul_f32_e32 v163, v171, v163
	v_fma_f32 v60, v60, v148, v134
	v_fma_f32 v61, v61, v149, v135
	v_fma_f32 v62, v62, v150, v146
	v_fma_f32 v63, v63, v151, v147
	v_fma_f32 v56, v56, v152, v156
	v_fma_f32 v57, v57, v153, v157
	v_fma_f32 v58, v58, v154, v162
	v_fma_f32 v59, v59, v155, v163
	ds_bpermute_b32 v134, v131, v52
	ds_bpermute_b32 v135, v131, v53
	ds_bpermute_b32 v146, v131, v54
	ds_bpermute_b32 v147, v131, v55
	ds_bpermute_b32 v156, v131, v48
	ds_bpermute_b32 v157, v131, v49
	ds_bpermute_b32 v162, v131, v50
	ds_bpermute_b32 v163, v131, v51
	v_cvt_pk_bf16_f32 v60, v60, v61
	v_cvt_pk_bf16_f32 v61, v62, v63
	v_cvt_pk_bf16_f32 v62, v56, v57
	v_cvt_pk_bf16_f32 v63, v58, v59
	global_store_dwordx4 v132, v[60:63], s[42:43] offset:0
	s_waitcnt lgkmcnt(0)
	v_mul_f32_e32 v134, v164, v134
	v_mul_f32_e32 v135, v165, v135
	v_mul_f32_e32 v146, v166, v146
	v_mul_f32_e32 v147, v167, v147
	v_mul_f32_e32 v156, v168, v156
	v_mul_f32_e32 v157, v169, v157
	v_mul_f32_e32 v162, v170, v162
	v_mul_f32_e32 v163, v171, v163
	v_fma_f32 v52, v52, v148, v134
	v_fma_f32 v53, v53, v149, v135
	v_fma_f32 v54, v54, v150, v146
	v_fma_f32 v55, v55, v151, v147
	v_fma_f32 v48, v48, v152, v156
	v_fma_f32 v49, v49, v153, v157
	v_fma_f32 v50, v50, v154, v162
	v_fma_f32 v51, v51, v155, v163
	v_cvt_pk_bf16_f32 v52, v52, v53
	v_cvt_pk_bf16_f32 v53, v54, v55
	v_cvt_pk_bf16_f32 v54, v48, v49
	v_cvt_pk_bf16_f32 v55, v50, v51
	global_store_dwordx4 v132, v[52:55], s[42:43] offset:256
	ds_bpermute_b32 v134, v131, v44
	ds_bpermute_b32 v135, v131, v45
	ds_bpermute_b32 v146, v131, v46
	ds_bpermute_b32 v147, v131, v47
	ds_bpermute_b32 v156, v131, v40
	ds_bpermute_b32 v157, v131, v41
	ds_bpermute_b32 v162, v131, v42
	ds_bpermute_b32 v163, v131, v43
	s_waitcnt vmcnt(10)
	v_cndmask_b32_e64 v172, v172, 1.0, s[40:41]
	v_cndmask_b32_e64 v173, v173, 1.0, s[40:41]
	v_cndmask_b32_e64 v174, v174, 1.0, s[40:41]
	v_cndmask_b32_e64 v175, v175, 1.0, s[40:41]
	v_cndmask_b32_e64 v176, v176, 1.0, s[40:41]
	v_cndmask_b32_e64 v177, v177, 1.0, s[40:41]
	v_cndmask_b32_e64 v178, v178, 1.0, s[40:41]
	v_cndmask_b32_e64 v179, v179, 1.0, s[40:41]
	v_xor_b32_e32 v180, v130, v180
	v_cndmask_b32_e64 v180, v180, 0, s[40:41]
	v_xor_b32_e32 v181, v130, v181
	v_cndmask_b32_e64 v181, v181, 0, s[40:41]
	v_xor_b32_e32 v182, v130, v182
	v_cndmask_b32_e64 v182, v182, 0, s[40:41]
	v_xor_b32_e32 v183, v130, v183
	v_cndmask_b32_e64 v183, v183, 0, s[40:41]
	v_xor_b32_e32 v184, v130, v184
	v_cndmask_b32_e64 v184, v184, 0, s[40:41]
	v_xor_b32_e32 v185, v130, v185
	v_cndmask_b32_e64 v185, v185, 0, s[40:41]
	v_xor_b32_e32 v186, v130, v186
	v_cndmask_b32_e64 v186, v186, 0, s[40:41]
	v_xor_b32_e32 v187, v130, v187
	v_cndmask_b32_e64 v187, v187, 0, s[40:41]
	s_mul_i32 s4, s73, 9
	v_add_u32_e32 v132, s4, v128
	s_waitcnt lgkmcnt(0)
	v_mul_f32_e32 v134, v180, v134
	v_mul_f32_e32 v135, v181, v135
	v_mul_f32_e32 v146, v182, v146
	v_mul_f32_e32 v147, v183, v147
	v_mul_f32_e32 v156, v184, v156
	v_mul_f32_e32 v157, v185, v157
	v_mul_f32_e32 v162, v186, v162
	v_mul_f32_e32 v163, v187, v163
	v_fma_f32 v44, v44, v172, v134
	v_fma_f32 v45, v45, v173, v135
	v_fma_f32 v46, v46, v174, v146
	v_fma_f32 v47, v47, v175, v147
	v_fma_f32 v40, v40, v176, v156
	v_fma_f32 v41, v41, v177, v157
	v_fma_f32 v42, v42, v178, v162
	v_fma_f32 v43, v43, v179, v163
	ds_bpermute_b32 v134, v131, v36
	ds_bpermute_b32 v135, v131, v37
	ds_bpermute_b32 v146, v131, v38
	ds_bpermute_b32 v147, v131, v39
	ds_bpermute_b32 v156, v131, v32
	ds_bpermute_b32 v157, v131, v33
	ds_bpermute_b32 v162, v131, v34
	ds_bpermute_b32 v163, v131, v35
	v_cvt_pk_bf16_f32 v44, v44, v45
	v_cvt_pk_bf16_f32 v45, v46, v47
	v_cvt_pk_bf16_f32 v46, v40, v41
	v_cvt_pk_bf16_f32 v47, v42, v43
	global_store_dwordx4 v132, v[44:47], s[42:43] offset:0
	s_waitcnt lgkmcnt(0)
	v_mul_f32_e32 v134, v180, v134
	v_mul_f32_e32 v135, v181, v135
	v_mul_f32_e32 v146, v182, v146
	v_mul_f32_e32 v147, v183, v147
	v_mul_f32_e32 v156, v184, v156
	v_mul_f32_e32 v157, v185, v157
	v_mul_f32_e32 v162, v186, v162
	v_mul_f32_e32 v163, v187, v163
	v_fma_f32 v36, v36, v172, v134
	v_fma_f32 v37, v37, v173, v135
	v_fma_f32 v38, v38, v174, v146
	v_fma_f32 v39, v39, v175, v147
	v_fma_f32 v32, v32, v176, v156
	v_fma_f32 v33, v33, v177, v157
	v_fma_f32 v34, v34, v178, v162
	v_fma_f32 v35, v35, v179, v163
	v_cvt_pk_bf16_f32 v36, v36, v37
	v_cvt_pk_bf16_f32 v37, v38, v39
	v_cvt_pk_bf16_f32 v38, v32, v33
	v_cvt_pk_bf16_f32 v39, v34, v35
	global_store_dwordx4 v132, v[36:39], s[42:43] offset:256
	ds_bpermute_b32 v134, v131, v28
	ds_bpermute_b32 v135, v131, v29
	ds_bpermute_b32 v146, v131, v30
	ds_bpermute_b32 v147, v131, v31
	ds_bpermute_b32 v156, v131, v24
	ds_bpermute_b32 v157, v131, v25
	ds_bpermute_b32 v162, v131, v26
	ds_bpermute_b32 v163, v131, v27
	s_waitcnt vmcnt(8)
	v_cndmask_b32_e64 v188, v188, 1.0, s[40:41]
	v_cndmask_b32_e64 v189, v189, 1.0, s[40:41]
	v_cndmask_b32_e64 v190, v190, 1.0, s[40:41]
	v_cndmask_b32_e64 v191, v191, 1.0, s[40:41]
	v_cndmask_b32_e64 v208, v208, 1.0, s[40:41]
	v_cndmask_b32_e64 v209, v209, 1.0, s[40:41]
	v_cndmask_b32_e64 v210, v210, 1.0, s[40:41]
	v_cndmask_b32_e64 v211, v211, 1.0, s[40:41]
	v_xor_b32_e32 v212, v130, v212
	v_cndmask_b32_e64 v212, v212, 0, s[40:41]
	v_xor_b32_e32 v213, v130, v213
	v_cndmask_b32_e64 v213, v213, 0, s[40:41]
	v_xor_b32_e32 v214, v130, v214
	v_cndmask_b32_e64 v214, v214, 0, s[40:41]
	v_xor_b32_e32 v215, v130, v215
	v_cndmask_b32_e64 v215, v215, 0, s[40:41]
	v_xor_b32_e32 v216, v130, v216
	v_cndmask_b32_e64 v216, v216, 0, s[40:41]
	v_xor_b32_e32 v217, v130, v217
	v_cndmask_b32_e64 v217, v217, 0, s[40:41]
	v_xor_b32_e32 v218, v130, v218
	v_cndmask_b32_e64 v218, v218, 0, s[40:41]
	v_xor_b32_e32 v219, v130, v219
	v_cndmask_b32_e64 v219, v219, 0, s[40:41]
	s_mul_i32 s4, s73, 10
	v_add_u32_e32 v132, s4, v128
	s_waitcnt lgkmcnt(0)
	v_mul_f32_e32 v134, v212, v134
	v_mul_f32_e32 v135, v213, v135
	v_mul_f32_e32 v146, v214, v146
	v_mul_f32_e32 v147, v215, v147
	v_mul_f32_e32 v156, v216, v156
	v_mul_f32_e32 v157, v217, v157
	v_mul_f32_e32 v162, v218, v162
	v_mul_f32_e32 v163, v219, v163
	v_fma_f32 v28, v28, v188, v134
	v_fma_f32 v29, v29, v189, v135
	v_fma_f32 v30, v30, v190, v146
	v_fma_f32 v31, v31, v191, v147
	v_fma_f32 v24, v24, v208, v156
	v_fma_f32 v25, v25, v209, v157
	v_fma_f32 v26, v26, v210, v162
	v_fma_f32 v27, v27, v211, v163
	ds_bpermute_b32 v134, v131, v20
	ds_bpermute_b32 v135, v131, v21
	ds_bpermute_b32 v146, v131, v22
	ds_bpermute_b32 v147, v131, v23
	ds_bpermute_b32 v156, v131, v16
	ds_bpermute_b32 v157, v131, v17
	ds_bpermute_b32 v162, v131, v18
	ds_bpermute_b32 v163, v131, v19
	v_cvt_pk_bf16_f32 v28, v28, v29
	v_cvt_pk_bf16_f32 v29, v30, v31
	v_cvt_pk_bf16_f32 v30, v24, v25
	v_cvt_pk_bf16_f32 v31, v26, v27
	global_store_dwordx4 v132, v[28:31], s[42:43] offset:0
	s_waitcnt lgkmcnt(0)
	v_mul_f32_e32 v134, v212, v134
	v_mul_f32_e32 v135, v213, v135
	v_mul_f32_e32 v146, v214, v146
	v_mul_f32_e32 v147, v215, v147
	v_mul_f32_e32 v156, v216, v156
	v_mul_f32_e32 v157, v217, v157
	v_mul_f32_e32 v162, v218, v162
	v_mul_f32_e32 v163, v219, v163
	v_fma_f32 v20, v20, v188, v134
	v_fma_f32 v21, v21, v189, v135
	v_fma_f32 v22, v22, v190, v146
	v_fma_f32 v23, v23, v191, v147
	v_fma_f32 v16, v16, v208, v156
	v_fma_f32 v17, v17, v209, v157
	v_fma_f32 v18, v18, v210, v162
	v_fma_f32 v19, v19, v211, v163
	v_cvt_pk_bf16_f32 v20, v20, v21
	v_cvt_pk_bf16_f32 v21, v22, v23
	v_cvt_pk_bf16_f32 v22, v16, v17
	v_cvt_pk_bf16_f32 v23, v18, v19
	global_store_dwordx4 v132, v[20:23], s[42:43] offset:256
	ds_bpermute_b32 v134, v131, v12
	ds_bpermute_b32 v135, v131, v13
	ds_bpermute_b32 v146, v131, v14
	ds_bpermute_b32 v147, v131, v15
	ds_bpermute_b32 v156, v131, v8
	ds_bpermute_b32 v157, v131, v9
	ds_bpermute_b32 v162, v131, v10
	ds_bpermute_b32 v163, v131, v11
	s_waitcnt vmcnt(6)
	v_cndmask_b32_e64 v220, v220, 1.0, s[40:41]
	v_cndmask_b32_e64 v221, v221, 1.0, s[40:41]
	v_cndmask_b32_e64 v222, v222, 1.0, s[40:41]
	v_cndmask_b32_e64 v223, v223, 1.0, s[40:41]
	v_cndmask_b32_e64 v224, v224, 1.0, s[40:41]
	v_cndmask_b32_e64 v225, v225, 1.0, s[40:41]
	v_cndmask_b32_e64 v226, v226, 1.0, s[40:41]
	v_cndmask_b32_e64 v227, v227, 1.0, s[40:41]
	v_xor_b32_e32 v228, v130, v228
	v_cndmask_b32_e64 v228, v228, 0, s[40:41]
	v_xor_b32_e32 v229, v130, v229
	v_cndmask_b32_e64 v229, v229, 0, s[40:41]
	v_xor_b32_e32 v230, v130, v230
	v_cndmask_b32_e64 v230, v230, 0, s[40:41]
	v_xor_b32_e32 v231, v130, v231
	v_cndmask_b32_e64 v231, v231, 0, s[40:41]
	v_xor_b32_e32 v232, v130, v232
	v_cndmask_b32_e64 v232, v232, 0, s[40:41]
	v_xor_b32_e32 v233, v130, v233
	v_cndmask_b32_e64 v233, v233, 0, s[40:41]
	v_xor_b32_e32 v234, v130, v234
	v_cndmask_b32_e64 v234, v234, 0, s[40:41]
	v_xor_b32_e32 v235, v130, v235
	v_cndmask_b32_e64 v235, v235, 0, s[40:41]
	s_mul_i32 s4, s73, 11
	v_add_u32_e32 v132, s4, v128
	s_waitcnt lgkmcnt(0)
	v_mul_f32_e32 v134, v228, v134
	v_mul_f32_e32 v135, v229, v135
	v_mul_f32_e32 v146, v230, v146
	v_mul_f32_e32 v147, v231, v147
	v_mul_f32_e32 v156, v232, v156
	v_mul_f32_e32 v157, v233, v157
	v_mul_f32_e32 v162, v234, v162
	v_mul_f32_e32 v163, v235, v163
	v_fma_f32 v12, v12, v220, v134
	v_fma_f32 v13, v13, v221, v135
	v_fma_f32 v14, v14, v222, v146
	v_fma_f32 v15, v15, v223, v147
	v_fma_f32 v8, v8, v224, v156
	v_fma_f32 v9, v9, v225, v157
	v_fma_f32 v10, v10, v226, v162
	v_fma_f32 v11, v11, v227, v163
	ds_bpermute_b32 v134, v131, v4
	ds_bpermute_b32 v135, v131, v5
	ds_bpermute_b32 v146, v131, v6
	ds_bpermute_b32 v147, v131, v7
	ds_bpermute_b32 v156, v131, v0
	ds_bpermute_b32 v157, v131, v1
	ds_bpermute_b32 v162, v131, v2
	ds_bpermute_b32 v163, v131, v3
	v_cvt_pk_bf16_f32 v12, v12, v13
	v_cvt_pk_bf16_f32 v13, v14, v15
	v_cvt_pk_bf16_f32 v14, v8, v9
	v_cvt_pk_bf16_f32 v15, v10, v11
	global_store_dwordx4 v132, v[12:15], s[42:43] offset:0
	s_waitcnt lgkmcnt(0)
	v_mul_f32_e32 v134, v228, v134
	v_mul_f32_e32 v135, v229, v135
	v_mul_f32_e32 v146, v230, v146
	v_mul_f32_e32 v147, v231, v147
	v_mul_f32_e32 v156, v232, v156
	v_mul_f32_e32 v157, v233, v157
	v_mul_f32_e32 v162, v234, v162
	v_mul_f32_e32 v163, v235, v163
	v_fma_f32 v4, v4, v220, v134
	v_fma_f32 v5, v5, v221, v135
	v_fma_f32 v6, v6, v222, v146
	v_fma_f32 v7, v7, v223, v147
	v_fma_f32 v0, v0, v224, v156
	v_fma_f32 v1, v1, v225, v157
	v_fma_f32 v2, v2, v226, v162
	v_fma_f32 v3, v3, v227, v163
	v_cvt_pk_bf16_f32 v4, v4, v5
	v_cvt_pk_bf16_f32 v5, v6, v7
	v_cvt_pk_bf16_f32 v6, v0, v1
	v_cvt_pk_bf16_f32 v7, v2, v3
	global_store_dwordx4 v132, v[4:7], s[42:43] offset:256
.Linb_done:
	s_andn2_b64 vcc, exec, s[36:37]
	s_mov_b64 s[4:5], -1
	s_branch .Linb_tail

.Linb_tail:
	s_cbranch_vccnz .LBB0_487
	s_andn2_b64 vcc, exec, s[6:7]
	s_cbranch_vccnz .LBB0_486
	s_barrier
	s_branch .LBB0_486
